# gate/up GEMM phases: per-cluster s_setprio toggling replaced by one static raise for waves 4..7 (the half that trails by one barrier), on top of the stacked file
# baseline (speedup 1.0000x reference)
; #define PG8_BAR __builtin_amdgcn_s_barrier()
; template <class Epi, class Sched, bool ALIGN_EPI = false, bool SP2 = false>
; __device__ __forceinline__ void gemm_phase(PG8_LAS unsigned char* lds, const Gemm g, const Sched& S, const Epi& E) {
;     ...
;     const int tid = tid_, wid = __builtin_amdgcn_readfirstlane(tid >> 6), lane = tid & 63, wr = wid >> 2, wc = wid & 3, fr = lane & 15, fq = lane >> 4;
;     const int K = g.K, LD = g.ld ? g.ld : g.K, nt = K / BK;
;     unsigned voffA[2], voffB[2];
; #pragma unroll
;     for (int i = 0; i < 2; ++i) { int R, C; stage_rc(tid * 16 + i * 8192, R, C); const int Rb = Epi::PERM ? ((R & ~31) + perm32(R & 31)) : R;
;         voffA[i] = (unsigned)(R * LD + C) * 2u; voffB[i] = (unsigned)(Rb * LD + C) * 2u; }
;     const size_t kstep = (size_t)(BK * 2);
;     const size_t hstep = (size_t)HALF * LD * 2;
;     const size_t tstep = 2 * hstep;
;     const unsigned ldsw = (unsigned)wid * 1024u;
;     const int aoff = lds_byte(wr * 64 + fr, fq * 8), boff = lds_byte(wc * 32 + fr, fq * 8);
;     ...
;     Unit cur, nxt; int ui = 0;
;     if (!S.next(0, cur)) return;
;     f32x4 acc[2][2][4][2];
; #pragma unroll
;     for (int a = 0; a < 2; ++a)
; #pragma unroll
;         for (int b = 0; b < 2; ++b)
; #pragma unroll
;             for (int m = 0; m < 4; ++m)
; #pragma unroll
;                 for (int n = 0; n < 2; ++n) acc[a][b][m][n] = (f32x4){0.f, 0.f, 0.f, 0.f};
;     bf16x8 At[4][2], B0[2][2], B1[2][2];
;     const size_t sstep = (size_t)K * 2;
;     const char* cA = (const char*)g.A + (size_t)cur.pm * tstep + (size_t)cur.pk * sstep; const char* cB = (const char*)g.Bt + (size_t)cur.pn * tstep + (size_t)cur.pk * sstep;
;     S.a_ready(cur);
;     if constexpr (SP2) {
;         PG8_STAGE(PG8_SB(0, 0), cB, voffB); PG8_STAGE(PG8_SB(0, 1), cB + hstep, voffB); PG8_STAGE(PG8_SA(0, 0), cA, voffA); PG8_STAGE(PG8_SA(0, 1), cA + hstep, voffA);
;         if (wr == 1) PG8_BAR;
;         PG8_WAIT_V(2); PG8_BAR;
;         PG8_STAGE(PG8_SB(1, 0), cB + kstep, voffB); PG8_STAGE(PG8_SA(1, 0), cA + kstep, voffA); PG8_STAGE(PG8_SB(1, 1), cB + hstep + kstep, voffB);
;         PG8_WAIT_V(6); PG8_BAR;
;     } else {
;         PG8_STAGE(PG8_SB(0, 0), cB, voffB); PG8_STAGE(PG8_SA(0, 0), cA, voffA); PG8_STAGE(PG8_SB(0, 1), cB + hstep, voffB); PG8_STAGE(PG8_SA(0, 1), cA + hstep, voffA);
;         if (wr == 1) PG8_BAR;
;         PG8_WAIT_V(4); PG8_BAR;
.LBB0_75:
	s_add_u32 s0, s44, 0x3000000
	s_addc_u32 s1, s45, 0
	v_writelane_b32 v254, s0, 13
	s_nop 1
	v_writelane_b32 v254, s1, 14
	s_add_u32 s0, s44, 0x7200000
	s_addc_u32 s1, s45, 0
	v_writelane_b32 v254, s0, 15
	s_cmp_lt_i32 s46, 2
	s_nop 0
	v_writelane_b32 v254, s1, 16
	s_cselect_b64 s[0:1], -1, 0
	s_cmp_gt_i32 s47, 1
	s_waitcnt lgkmcnt(0)
	s_cselect_b64 s[2:3], -1, 0
	s_and_b64 s[0:1], s[0:1], s[2:3]
	s_andn2_b64 vcc, exec, s[0:1]
	s_cbranch_vccnz .LBB0_192
	v_mov_b32_e32 v11, v0
	s_cmpk_gt_i32 s33, 0xb57
	v_readfirstlane_b32 s3, v11
	s_cbranch_scc1 .LBB0_92
	v_readlane_b32 s98, v254, 9
	s_cmp_lt_u32 s98, 4
	s_cbranch_scc1 .Lmy_prio_p1
	s_setprio 1
.Lmy_prio_p1:
	v_lshlrev_b32_e32 v1, 4, v11
	v_add_u32_e32 v2, 0x2000, v1
	v_ashrrev_i32_e32 v3, 31, v2
	v_lshrrev_b32_e32 v3, 22, v3
	v_add_u32_e32 v3, v2, v3
	v_ashrrev_i32_e32 v10, 10, v3
	v_mul_i32_i24_e32 v3, 0x400, v10
	v_sub_u32_e32 v2, v2, v3
	v_lshrrev_b32_e32 v3, 4, v2
	v_bitop3_b32 v2, v3, v2, 32 bitop3:0x6c
	v_ashrrev_i32_e32 v3, 31, v2
	v_lshrrev_b32_e32 v3, 26, v3
	v_add_u32_e32 v3, v2, v3
	v_lshlrev_b32_e32 v4, 3, v10
	v_ashrrev_i32_e32 v12, 6, v3
	v_and_b32_e32 v4, -16, v4
	v_add_u32_e32 v4, v12, v4
	v_and_b32_e32 v5, 3, v12
	s_mov_b32 s2, 0x1fffe0
	v_lshrrev_b32_e32 v6, 2, v4
	v_lshlrev_b32_e32 v7, 1, v4
	v_and_b32_e32 v3, 0xc0, v3
	v_and_or_b32 v5, v4, s2, v5
	v_and_b32_e32 v6, 4, v6
	v_and_b32_e32 v7, 24, v7
	v_sub_u32_e32 v2, v2, v3
	v_mov_b32_e32 v3, 1
	v_or3_b32 v5, v5, v6, v7
	v_lshlrev_b32_e32 v6, 5, v10
	v_ashrrev_i16_sdwa v2, v3, sext(v2) dst_sel:DWORD dst_unused:UNUSED_PAD src0_sel:DWORD src1_sel:BYTE_0
	v_and_b32_e32 v6, 32, v6
	v_bfe_i32 v13, v2, 0, 16
	v_add_lshl_u32 v2, v6, v13, 1
	v_lshl_add_u32 v130, v5, 11, v2
	v_lshl_add_u32 v132, v4, 11, v2
	v_bfe_i32 v2, v11, 27, 1
	v_lshrrev_b32_e32 v2, 22, v2
	v_add_u32_e32 v2, v1, v2
	v_and_b32_e32 v2, 0xfffffc00, v2
	v_sub_u32_e32 v1, v1, v2
	v_lshrrev_b32_e32 v2, 4, v1
	v_ashrrev_i32_e32 v4, 31, v11
	v_bitop3_b32 v1, v2, v1, 32 bitop3:0x6c
	v_lshrrev_b32_e32 v4, 26, v4
	v_ashrrev_i32_e32 v2, 31, v1
	v_add_u32_e32 v4, v11, v4
	v_lshrrev_b32_e32 v2, 26, v2
	v_ashrrev_i32_e32 v15, 6, v4
	v_add_u32_e32 v2, v1, v2
	v_lshlrev_b32_e32 v4, 3, v15
	s_add_u32 s0, s44, 0x200000
	v_ashrrev_i32_e32 v14, 6, v2
	v_and_b32_e32 v4, -16, v4
	s_addc_u32 s1, s45, 0
	v_add_u32_e32 v4, v14, v4
	v_and_b32_e32 v5, 3, v14
	s_ashr_i32 s27, s33, 31
	v_and_or_b32 v5, v4, s2, v5
	s_lshr_b32 s2, s27, 29
	s_add_i32 s2, s33, s2
	s_ashr_i32 s6, s3, 6
	s_ashr_i32 s4, s2, 3
	s_and_b32 s2, s2, -8
	s_ashr_i32 s8, s3, 8
	s_lshl_b32 s26, s6, 10
	s_sub_i32 s2, s33, s2
	s_cmp_lt_i32 s2, 0
	s_movk_i32 s28, 0x16c
	s_cselect_b32 s5, s28, 0x16b
	s_mul_i32 s2, s2, s5
	s_add_i32 s2, s2, s4
	s_mul_hi_i32 s4, s2, 0x2e8ba2e9
	s_lshr_b32 s5, s4, 31
	s_ashr_i32 s4, s4, 5
	v_lshrrev_b32_e32 v6, 2, v4
	v_lshlrev_b32_e32 v7, 1, v4
	v_and_b32_e32 v2, 0xc0, v2
	s_add_i32 s4, s4, s5
	v_and_b32_e32 v6, 4, v6
	v_and_b32_e32 v7, 24, v7
	v_sub_u32_e32 v1, v1, v2
	s_lshl_b32 s7, s4, 3
	v_or3_b32 v5, v5, v6, v7
	v_lshlrev_b32_e32 v6, 5, v15
	v_ashrrev_i16_sdwa v1, v3, sext(v1) dst_sel:DWORD dst_unused:UNUSED_PAD src0_sel:DWORD src1_sel:BYTE_0
	s_sub_i32 s5, 0x84, s7
	s_mulk_i32 s4, 0xb0
	v_and_b32_e32 v6, 32, v6
	v_bfe_i32 v16, v1, 0, 16
	s_min_u32 s9, s5, 8
	s_sub_i32 s10, s2, s4
	v_add_lshl_u32 v1, v6, v16, 1
	s_sext_i32_i16 s2, s10
	v_cvt_f32_ubyte0_e32 v3, s9
	v_lshl_add_u32 v134, v5, 11, v1
	v_cvt_f32_i32_e32 v2, s2
	v_rcp_iflag_f32_e32 v5, v3
	v_lshl_add_u32 v136, v4, 11, v1
	s_ashr_i32 s2, s2, 30
	s_or_b32 s2, s2, 1
	v_mul_f32_e32 v1, v2, v5
	v_trunc_f32_e32 v1, v1
	v_fma_f32 v2, -v1, v3, v2
	v_cvt_i32_f32_e32 v1, v1
	v_cmp_ge_f32_e64 s[4:5], |v2|, v3
	s_and_b64 s[4:5], s[4:5], exec
	s_cselect_b32 s2, s2, 0
	v_readfirstlane_b32 s4, v1
	s_add_i32 s2, s4, s2
	s_mul_i32 s4, s2, s9
	s_sub_i32 s4, s10, s4
	s_sext_i32_i16 s4, s4
	s_add_i32 s18, s7, s4
	s_ashr_i32 s19, s18, 31
	s_bfe_i64 s[10:11], s[2:3], 0x100000
	s_lshl_b64 s[4:5], s[18:19], 19
	s_lshl_b64 s[10:11], s[10:11], 19
	s_add_u32 s22, s0, s10
	s_addc_u32 s23, s1, s11
	s_add_i32 s19, s26, 0
	s_add_i32 m0, s19, 0x10000
	v_mov_b32_e32 v135, 0
	global_load_lds_dwordx4 v134, s[22:23]
	s_add_i32 m0, s19, 0x12000
	s_add_u32 s10, s22, 0x40000
	global_load_lds_dwordx4 v130, s[22:23]
	s_addc_u32 s11, s23, 0
	s_add_i32 m0, s19, 0x14000
	v_mov_b32_e32 v131, v135
	global_load_lds_dwordx4 v134, s[10:11]
	s_add_i32 m0, s19, 0x16000
	v_mov_b32_e32 v137, v135
	global_load_lds_dwordx4 v130, s[10:11]
	v_readlane_b32 s10, v254, 13
	v_readlane_b32 s11, v254, 14
	s_add_u32 s20, s10, s4
	s_addc_u32 s21, s11, s5
	s_add_i32 s29, s19, 0x2000
	s_mov_b32 m0, s19
	s_add_u32 s4, s20, 0x40000
	global_load_lds_dwordx4 v136, s[20:21]
	s_mov_b32 m0, s29
	s_addc_u32 s5, s21, 0
	s_add_i32 s30, s19, 0x4000
	global_load_lds_dwordx4 v132, s[20:21]
	s_mov_b32 m0, s30
	s_add_i32 s31, s19, 0x6000
	global_load_lds_dwordx4 v136, s[4:5]
	s_mov_b32 m0, s31
	v_mov_b32_e32 v133, v135
	global_load_lds_dwordx4 v132, s[4:5]
	s_cmp_eq_u32 s8, 1
	s_mov_b32 s34, 0
	v_lshl_add_u64 v[8:9], s[22:23], 0, v[134:135]
	v_lshl_add_u64 v[6:7], s[22:23], 0, v[130:131]
	v_lshl_add_u64 v[2:3], s[20:21], 0, v[136:137]
	s_cselect_b64 s[4:5], -1, 0
	s_cmp_lg_u32 s8, 1
	v_lshl_add_u64 v[4:5], s[20:21], 0, v[132:133]
	s_cbranch_scc1 .LBB0_79
	s_barrier

; #define PG8_STAGE(bufoff, gbase, voff) do { _Pragma("unroll") for (int _i = 0; _i < 2; ++_i) \
;         __builtin_amdgcn_global_load_lds((const unsigned*)((const char*)(gbase) + (voff)[_i]), (PG8_LAS unsigned*)(lds + (bufoff) + ldsw + _i * 8192), 16, 0, 0); } while (0)
; #define PG8_LDA(dst, b, h) do { _Pragma("unroll") for (int m = 0; m < 4; ++m) _Pragma("unroll") for (int k = 0; k < 2; ++k) dst[m][k] = *(const PG8_LAS bf16x8*)(lds + PG8_SA(b, h) + aoff + m * 2048 + k * 1024); } while (0)
; #define PG8_LDB(dst, b, h) do { _Pragma("unroll") for (int n = 0; n < 2; ++n) _Pragma("unroll") for (int k = 0; k < 2; ++k) dst[n][k] = *(const PG8_LAS bf16x8*)(lds + PG8_SB(b, h) + boff + n * 2048 + k * 1024); } while (0)
; #define PG8_MMA(ai, bj, At, Bt) do { __builtin_amdgcn_s_setprio(1); _Pragma("unroll") for (int m = 0; m < 4; ++m) _Pragma("unroll") for (int n = 0; n < 2; ++n) _Pragma("unroll") for (int k = 0; k < 2; ++k) \
;         acc[ai][bj][m][n] = __builtin_amdgcn_mfma_f32_16x16x32_bf16(Bt[n][k], At[m][k], acc[ai][bj][m][n], 0, 0, 0); __builtin_amdgcn_s_setprio(0); } while (0)
; #define PG8_WAIT_V(n) asm volatile("s_waitcnt vmcnt(" #n ")" ::: "memory")
; #define PG8_WAIT_L(n) asm volatile("s_waitcnt lgkmcnt(" #n ")" ::: "memory")
; #define PG8_BAR __builtin_amdgcn_s_barrier()
; #define PG8_SCHED __builtin_amdgcn_sched_barrier(0)
; template <class Epi, class Sched, bool ALIGN_EPI = false, bool SP2 = false>
; __device__ __forceinline__ void gemm_phase(PG8_LAS unsigned char* lds, const Gemm g, const Sched& S, const Epi& E) {
;     ...
;             PG8_LDB(B0, 0, 0); PG8_LDB(B1, 0, 1); PG8_SCHED; PG8_LDA(At, 0, 0); PG8_STAGE(PG8_SA(1, 1), a1 + hstep, voffA);
;             PG8_WAIT_V(8); PG8_WAIT_L(0); PG8_BAR; PG8_MMA(0, 0, At, B0); PG8_MMA(0, 1, At, B1); PG8_BAR; PG8_SCHED;
;             PG8_LDA(At, 0, 1); PG8_STAGE(PG8_SB(0, 0), b2, voffB); PG8_STAGE(PG8_SB(0, 1), b2 + hstep, voffB); PG8_STAGE(PG8_SA(0, 0), a2, voffA);
;             PG8_WAIT_V(8); PG8_WAIT_L(0); PG8_BAR; PG8_MMA(1, 0, At, B0); PG8_MMA(1, 1, At, B1); PG8_BAR; PG8_SCHED;
.LBB0_85:
	ds_read_b128 v[146:149], v152
	ds_read_b128 v[156:159], v152 offset:1024
	ds_read_b128 v[160:163], v152 offset:2048
	ds_read_b128 v[164:167], v152 offset:3072
	ds_read_b128 v[168:171], v153
	ds_read_b128 v[172:175], v153 offset:1024
	ds_read_b128 v[176:179], v153 offset:2048
	ds_read_b128 v[180:183], v153 offset:3072
	s_add_u32 s22, s20, 0xfffc0080
	s_addc_u32 s23, s21, -1
	s_cmp_eq_u32 s50, 12
	s_cselect_b32 s25, s13, s23
	s_cselect_b32 s24, s42, s22
	s_cselect_b32 s23, s11, s49
	s_cselect_b32 s22, s43, s48
	v_lshl_add_u64 v[184:185], s[20:21], 0, v[138:139]
	s_add_i32 m0, s19, 0xc000
	ds_read_b128 v[188:191], v154
	ds_read_b128 v[192:195], v154 offset:1024
	ds_read_b128 v[196:199], v154 offset:2048
	ds_read_b128 v[200:203], v154 offset:3072
	ds_read_b128 v[204:207], v154 offset:4096
	ds_read_b128 v[208:211], v154 offset:5120
	ds_read_b128 v[212:215], v154 offset:6144
	ds_read_b128 v[216:219], v154 offset:7168
	global_load_lds_dwordx4 v[184:185], off
	v_lshl_add_u64 v[184:185], s[20:21], 0, v[140:141]
	s_add_i32 m0, s19, 0xe000
	s_nop 0
	global_load_lds_dwordx4 v[184:185], off
	s_waitcnt vmcnt(8)
	s_waitcnt lgkmcnt(0)
	s_barrier
	s_waitcnt lgkmcnt(0)
	v_mfma_f32_16x16x32_bf16 v[126:129], v[146:149], v[188:191], v[126:129]
	v_mfma_f32_16x16x32_bf16 v[122:125], v[160:163], v[188:191], v[122:125]
	v_mfma_f32_16x16x32_bf16 v[110:113], v[146:149], v[196:199], v[110:113]
	v_mfma_f32_16x16x32_bf16 v[106:109], v[160:163], v[196:199], v[106:109]
	v_mfma_f32_16x16x32_bf16 v[94:97], v[146:149], v[204:207], v[94:97]
	v_mfma_f32_16x16x32_bf16 v[90:93], v[160:163], v[204:207], v[90:93]
	v_mfma_f32_16x16x32_bf16 v[78:81], v[146:149], v[212:215], v[78:81]
	v_mfma_f32_16x16x32_bf16 v[74:77], v[160:163], v[212:215], v[74:77]
	v_mfma_f32_16x16x32_bf16 v[126:129], v[156:159], v[192:195], v[126:129]
	v_mfma_f32_16x16x32_bf16 v[122:125], v[164:167], v[192:195], v[122:125]
	v_mfma_f32_16x16x32_bf16 v[110:113], v[156:159], v[200:203], v[110:113]
	v_mfma_f32_16x16x32_bf16 v[106:109], v[164:167], v[200:203], v[106:109]
	v_mfma_f32_16x16x32_bf16 v[94:97], v[156:159], v[208:211], v[94:97]
	v_mfma_f32_16x16x32_bf16 v[90:93], v[164:167], v[208:211], v[90:93]
	v_mfma_f32_16x16x32_bf16 v[78:81], v[156:159], v[216:219], v[78:81]
	v_mfma_f32_16x16x32_bf16 v[74:77], v[164:167], v[216:219], v[74:77]
	v_mfma_f32_16x16x32_bf16 v[118:121], v[168:171], v[188:191], v[118:121]
	v_mfma_f32_16x16x32_bf16 v[114:117], v[176:179], v[188:191], v[114:117]
	v_mfma_f32_16x16x32_bf16 v[102:105], v[168:171], v[196:199], v[102:105]
	v_mfma_f32_16x16x32_bf16 v[98:101], v[176:179], v[196:199], v[98:101]
	v_mfma_f32_16x16x32_bf16 v[86:89], v[168:171], v[204:207], v[86:89]
	v_mfma_f32_16x16x32_bf16 v[82:85], v[176:179], v[204:207], v[82:85]
	v_mfma_f32_16x16x32_bf16 v[70:73], v[168:171], v[212:215], v[70:73]
	v_mfma_f32_16x16x32_bf16 v[66:69], v[176:179], v[212:215], v[66:69]
	v_mfma_f32_16x16x32_bf16 v[118:121], v[172:175], v[192:195], v[118:121]
	v_mfma_f32_16x16x32_bf16 v[114:117], v[180:183], v[192:195], v[114:117]
	v_mfma_f32_16x16x32_bf16 v[102:105], v[172:175], v[200:203], v[102:105]
	v_mfma_f32_16x16x32_bf16 v[98:101], v[180:183], v[200:203], v[98:101]
	v_mfma_f32_16x16x32_bf16 v[86:89], v[172:175], v[208:211], v[86:89]
	v_mfma_f32_16x16x32_bf16 v[82:85], v[180:183], v[208:211], v[82:85]
	v_mfma_f32_16x16x32_bf16 v[70:73], v[172:175], v[216:219], v[70:73]
	v_mfma_f32_16x16x32_bf16 v[66:69], v[180:183], v[216:219], v[66:69]
	s_barrier
	s_add_i32 s51, s38, s26
	v_lshl_add_u64 v[184:185], s[22:23], 0, v[134:135]
	s_mov_b32 m0, s51
	ds_read_b128 v[188:191], v154 offset:16384
	ds_read_b128 v[192:195], v154 offset:17408
	ds_read_b128 v[196:199], v154 offset:18432
	ds_read_b128 v[200:203], v154 offset:19456
	ds_read_b128 v[204:207], v154 offset:20480
	ds_read_b128 v[208:211], v154 offset:21504
	ds_read_b128 v[212:215], v154 offset:22528
	ds_read_b128 v[216:219], v154 offset:23552
	global_load_lds_dwordx4 v[184:185], off
	s_add_i32 m0, s51, 0x2000
	s_add_u32 s52, s22, 0x40000
	v_lshl_add_u64 v[220:221], s[22:23], 0, v[130:131]
	s_addc_u32 s53, s23, 0
	s_add_i32 s51, s39, s26
	global_load_lds_dwordx4 v[220:221], off
	v_lshl_add_u64 v[222:223], s[52:53], 0, v[134:135]
	s_mov_b32 m0, s51
	v_lshl_add_u64 v[224:225], s[24:25], 0, v[132:133]
	global_load_lds_dwordx4 v[222:223], off
	v_lshl_add_u64 v[222:223], s[52:53], 0, v[130:131]
	s_add_i32 m0, s51, 0x2000
	s_nop 0
	global_load_lds_dwordx4 v[222:223], off
	v_lshl_add_u64 v[222:223], s[24:25], 0, v[136:137]
	s_mov_b32 m0, s19
	s_nop 0
	global_load_lds_dwordx4 v[222:223], off
	s_mov_b32 m0, s29
	s_nop 0
	global_load_lds_dwordx4 v[224:225], off
	s_waitcnt vmcnt(8)
	s_waitcnt lgkmcnt(0)
	s_barrier
; #define PG8_STAGE(bufoff, gbase, voff) do { _Pragma("unroll") for (int _i = 0; _i < 2; ++_i) \
;         __builtin_amdgcn_global_load_lds((const unsigned*)((const char*)(gbase) + (voff)[_i]), (PG8_LAS unsigned*)(lds + (bufoff) + ldsw + _i * 8192), 16, 0, 0); } while (0)
; #define PG8_LDA(dst, b, h) do { _Pragma("unroll") for (int m = 0; m < 4; ++m) _Pragma("unroll") for (int k = 0; k < 2; ++k) dst[m][k] = *(const PG8_LAS bf16x8*)(lds + PG8_SA(b, h) + aoff + m * 2048 + k * 1024); } while (0)
; #define PG8_LDB(dst, b, h) do { _Pragma("unroll") for (int n = 0; n < 2; ++n) _Pragma("unroll") for (int k = 0; k < 2; ++k) dst[n][k] = *(const PG8_LAS bf16x8*)(lds + PG8_SB(b, h) + boff + n * 2048 + k * 1024); } while (0)
; #define PG8_MMA(ai, bj, At, Bt) do { __builtin_amdgcn_s_setprio(1); _Pragma("unroll") for (int m = 0; m < 4; ++m) _Pragma("unroll") for (int n = 0; n < 2; ++n) _Pragma("unroll") for (int k = 0; k < 2; ++k) \
;         acc[ai][bj][m][n] = __builtin_amdgcn_mfma_f32_16x16x32_bf16(Bt[n][k], At[m][k], acc[ai][bj][m][n], 0, 0, 0); __builtin_amdgcn_s_setprio(0); } while (0)
; #define PG8_WAIT_V(n) asm volatile("s_waitcnt vmcnt(" #n ")" ::: "memory")
; #define PG8_WAIT_L(n) asm volatile("s_waitcnt lgkmcnt(" #n ")" ::: "memory")
; #define PG8_BAR __builtin_amdgcn_s_barrier()
; #define PG8_SCHED __builtin_amdgcn_sched_barrier(0)
; template <class Epi, class Sched, bool ALIGN_EPI = false, bool SP2 = false>
; __device__ __forceinline__ void gemm_phase(PG8_LAS unsigned char* lds, const Gemm g, const Sched& S, const Epi& E) {
;     ...
;             PG8_WAIT_V(8); PG8_WAIT_L(0); PG8_BAR; PG8_MMA(0, 0, At, B0); PG8_MMA(0, 1, At, B1); PG8_BAR; PG8_SCHED;
;             PG8_LDA(At, 0, 1); PG8_STAGE(PG8_SB(0, 0), b2, voffB); PG8_STAGE(PG8_SB(0, 1), b2 + hstep, voffB); PG8_STAGE(PG8_SA(0, 0), a2, voffA);
;             PG8_WAIT_V(8); PG8_WAIT_L(0); PG8_BAR; PG8_MMA(1, 0, At, B0); PG8_MMA(1, 1, At, B1); PG8_BAR; PG8_SCHED;
;             PG8_LDB(B0, 1, 0); PG8_LDB(B1, 1, 1); PG8_SCHED; PG8_LDA(At, 1, 0); PG8_STAGE(PG8_SA(0, 1), a2 + hstep, voffA);
;             PG8_WAIT_V(8); PG8_WAIT_L(0); PG8_BAR; PG8_MMA(0, 0, At, B0); PG8_MMA(0, 1, At, B1); PG8_BAR; PG8_SCHED;
	s_waitcnt lgkmcnt(0)
	v_mfma_f32_16x16x32_bf16 v[62:65], v[146:149], v[188:191], v[62:65]
	v_mfma_f32_16x16x32_bf16 v[58:61], v[160:163], v[188:191], v[58:61]
	v_mfma_f32_16x16x32_bf16 v[46:49], v[146:149], v[196:199], v[46:49]
	v_mfma_f32_16x16x32_bf16 v[42:45], v[160:163], v[196:199], v[42:45]
	v_mfma_f32_16x16x32_bf16 v[30:33], v[146:149], v[204:207], v[30:33]
	v_mfma_f32_16x16x32_bf16 v[26:29], v[160:163], v[204:207], v[26:29]
	v_mfma_f32_16x16x32_bf16 v[14:17], v[146:149], v[212:215], v[14:17]
	v_mfma_f32_16x16x32_bf16 v[10:13], v[160:163], v[212:215], v[10:13]
	v_mfma_f32_16x16x32_bf16 v[62:65], v[156:159], v[192:195], v[62:65]
	v_mfma_f32_16x16x32_bf16 v[58:61], v[164:167], v[192:195], v[58:61]
	v_mfma_f32_16x16x32_bf16 v[46:49], v[156:159], v[200:203], v[46:49]
	v_mfma_f32_16x16x32_bf16 v[42:45], v[164:167], v[200:203], v[42:45]
	v_mfma_f32_16x16x32_bf16 v[30:33], v[156:159], v[208:211], v[30:33]
	v_mfma_f32_16x16x32_bf16 v[26:29], v[164:167], v[208:211], v[26:29]
	v_mfma_f32_16x16x32_bf16 v[14:17], v[156:159], v[216:219], v[14:17]
	v_mfma_f32_16x16x32_bf16 v[10:13], v[164:167], v[216:219], v[10:13]
	v_mfma_f32_16x16x32_bf16 v[54:57], v[168:171], v[188:191], v[54:57]
	v_mfma_f32_16x16x32_bf16 v[50:53], v[176:179], v[188:191], v[50:53]
	v_mfma_f32_16x16x32_bf16 v[38:41], v[168:171], v[196:199], v[38:41]
	v_mfma_f32_16x16x32_bf16 v[34:37], v[176:179], v[196:199], v[34:37]
	v_mfma_f32_16x16x32_bf16 v[22:25], v[168:171], v[204:207], v[22:25]
	v_mfma_f32_16x16x32_bf16 v[18:21], v[176:179], v[204:207], v[18:21]
	v_mfma_f32_16x16x32_bf16 v[6:9], v[168:171], v[212:215], v[6:9]
	v_mfma_f32_16x16x32_bf16 v[2:5], v[176:179], v[212:215], v[2:5]
	v_mfma_f32_16x16x32_bf16 v[54:57], v[172:175], v[192:195], v[54:57]
	v_mfma_f32_16x16x32_bf16 v[50:53], v[180:183], v[192:195], v[50:53]
	v_mfma_f32_16x16x32_bf16 v[38:41], v[172:175], v[200:203], v[38:41]
	v_mfma_f32_16x16x32_bf16 v[34:37], v[180:183], v[200:203], v[34:37]
	v_mfma_f32_16x16x32_bf16 v[22:25], v[172:175], v[208:211], v[22:25]
	v_mfma_f32_16x16x32_bf16 v[18:21], v[180:183], v[208:211], v[18:21]
	v_mfma_f32_16x16x32_bf16 v[6:9], v[172:175], v[216:219], v[6:9]
	v_mfma_f32_16x16x32_bf16 v[2:5], v[180:183], v[216:219], v[2:5]
	s_barrier
	s_add_i32 s51, 0, 0x18000
	v_add_u32_e32 v155, s51, v150
	s_add_i32 s52, 0, 0x1c000
	ds_read_b128 v[146:149], v155
	ds_read_b128 v[156:159], v155 offset:1024
	ds_read_b128 v[160:163], v155 offset:2048
	ds_read_b128 v[164:167], v155 offset:3072
	v_add_u32_e32 v155, s52, v150
	ds_read_b128 v[168:171], v155
	ds_read_b128 v[172:175], v155 offset:1024
	ds_read_b128 v[176:179], v155 offset:2048
	ds_read_b128 v[180:183], v155 offset:3072
	s_add_u32 s24, s24, 0x40000
	s_addc_u32 s25, s25, 0
	s_mov_b32 m0, s30
	v_lshl_add_u64 v[226:227], s[24:25], 0, v[136:137]
	ds_read_b128 v[188:191], v154 offset:32768
	ds_read_b128 v[192:195], v154 offset:33792
	ds_read_b128 v[196:199], v154 offset:34816
	ds_read_b128 v[200:203], v154 offset:35840
	ds_read_b128 v[204:207], v154 offset:36864
	ds_read_b128 v[208:211], v154 offset:37888
	ds_read_b128 v[212:215], v154 offset:38912
	ds_read_b128 v[216:219], v154 offset:39936
	global_load_lds_dwordx4 v[226:227], off
	v_lshl_add_u64 v[226:227], s[24:25], 0, v[132:133]
	s_mov_b32 m0, s31
	s_nop 0
	global_load_lds_dwordx4 v[226:227], off
	s_waitcnt vmcnt(8)
	s_waitcnt lgkmcnt(0)
	s_barrier
	s_waitcnt lgkmcnt(0)
	v_mfma_f32_16x16x32_bf16 v[126:129], v[146:149], v[188:191], v[126:129]
	v_mfma_f32_16x16x32_bf16 v[122:125], v[160:163], v[188:191], v[122:125]
	v_mfma_f32_16x16x32_bf16 v[110:113], v[146:149], v[196:199], v[110:113]
	v_mfma_f32_16x16x32_bf16 v[106:109], v[160:163], v[196:199], v[106:109]
	v_mfma_f32_16x16x32_bf16 v[94:97], v[146:149], v[204:207], v[94:97]
	v_mfma_f32_16x16x32_bf16 v[90:93], v[160:163], v[204:207], v[90:93]
	v_mfma_f32_16x16x32_bf16 v[78:81], v[146:149], v[212:215], v[78:81]
	v_mfma_f32_16x16x32_bf16 v[74:77], v[160:163], v[212:215], v[74:77]
	v_mfma_f32_16x16x32_bf16 v[126:129], v[156:159], v[192:195], v[126:129]
	v_mfma_f32_16x16x32_bf16 v[122:125], v[164:167], v[192:195], v[122:125]
	v_mfma_f32_16x16x32_bf16 v[110:113], v[156:159], v[200:203], v[110:113]
	v_mfma_f32_16x16x32_bf16 v[106:109], v[164:167], v[200:203], v[106:109]
	v_mfma_f32_16x16x32_bf16 v[94:97], v[156:159], v[208:211], v[94:97]
	v_mfma_f32_16x16x32_bf16 v[90:93], v[164:167], v[208:211], v[90:93]
	v_mfma_f32_16x16x32_bf16 v[78:81], v[156:159], v[216:219], v[78:81]
	v_mfma_f32_16x16x32_bf16 v[74:77], v[164:167], v[216:219], v[74:77]
	v_mfma_f32_16x16x32_bf16 v[118:121], v[168:171], v[188:191], v[118:121]
	v_mfma_f32_16x16x32_bf16 v[114:117], v[176:179], v[188:191], v[114:117]
	v_mfma_f32_16x16x32_bf16 v[102:105], v[168:171], v[196:199], v[102:105]
	v_mfma_f32_16x16x32_bf16 v[98:101], v[176:179], v[196:199], v[98:101]
	v_mfma_f32_16x16x32_bf16 v[86:89], v[168:171], v[204:207], v[86:89]
	v_mfma_f32_16x16x32_bf16 v[82:85], v[176:179], v[204:207], v[82:85]
	v_mfma_f32_16x16x32_bf16 v[70:73], v[168:171], v[212:215], v[70:73]
	v_mfma_f32_16x16x32_bf16 v[66:69], v[176:179], v[212:215], v[66:69]
	v_mfma_f32_16x16x32_bf16 v[118:121], v[172:175], v[192:195], v[118:121]
	v_mfma_f32_16x16x32_bf16 v[114:117], v[180:183], v[192:195], v[114:117]
	v_mfma_f32_16x16x32_bf16 v[102:105], v[172:175], v[200:203], v[102:105]
	v_mfma_f32_16x16x32_bf16 v[98:101], v[180:183], v[200:203], v[98:101]
	v_mfma_f32_16x16x32_bf16 v[86:89], v[172:175], v[208:211], v[86:89]
	v_mfma_f32_16x16x32_bf16 v[82:85], v[180:183], v[208:211], v[82:85]
	v_mfma_f32_16x16x32_bf16 v[70:73], v[172:175], v[216:219], v[70:73]
	v_mfma_f32_16x16x32_bf16 v[66:69], v[180:183], v[216:219], v[66:69]
	s_barrier
; #define PG8_STAGE(bufoff, gbase, voff) do { _Pragma("unroll") for (int _i = 0; _i < 2; ++_i) \
;         __builtin_amdgcn_global_load_lds((const unsigned*)((const char*)(gbase) + (voff)[_i]), (PG8_LAS unsigned*)(lds + (bufoff) + ldsw + _i * 8192), 16, 0, 0); } while (0)
; #define PG8_LDA(dst, b, h) do { _Pragma("unroll") for (int m = 0; m < 4; ++m) _Pragma("unroll") for (int k = 0; k < 2; ++k) dst[m][k] = *(const PG8_LAS bf16x8*)(lds + PG8_SA(b, h) + aoff + m * 2048 + k * 1024); } while (0)
; #define PG8_LDB(dst, b, h) do { _Pragma("unroll") for (int n = 0; n < 2; ++n) _Pragma("unroll") for (int k = 0; k < 2; ++k) dst[n][k] = *(const PG8_LAS bf16x8*)(lds + PG8_SB(b, h) + boff + n * 2048 + k * 1024); } while (0)
; #define PG8_MMA(ai, bj, At, Bt) do { __builtin_amdgcn_s_setprio(1); _Pragma("unroll") for (int m = 0; m < 4; ++m) _Pragma("unroll") for (int n = 0; n < 2; ++n) _Pragma("unroll") for (int k = 0; k < 2; ++k) \
;         acc[ai][bj][m][n] = __builtin_amdgcn_mfma_f32_16x16x32_bf16(Bt[n][k], At[m][k], acc[ai][bj][m][n], 0, 0, 0); __builtin_amdgcn_s_setprio(0); } while (0)
; #define PG8_WAIT_V(n) asm volatile("s_waitcnt vmcnt(" #n ")" ::: "memory")
; #define PG8_WAIT_L(n) asm volatile("s_waitcnt lgkmcnt(" #n ")" ::: "memory")
; #define PG8_BAR __builtin_amdgcn_s_barrier()
; #define PG8_SCHED __builtin_amdgcn_sched_barrier(0)
; template <class Epi, class Sched, bool ALIGN_EPI = false, bool SP2 = false>
; __device__ __forceinline__ void gemm_phase(PG8_LAS unsigned char* lds, const Gemm g, const Sched& S, const Epi& E) {
;     ...
;             PG8_LDB(B0, 1, 0); PG8_LDB(B1, 1, 1); PG8_SCHED; PG8_LDA(At, 1, 0); PG8_STAGE(PG8_SA(0, 1), a2 + hstep, voffA);
;             PG8_WAIT_V(8); PG8_WAIT_L(0); PG8_BAR; PG8_MMA(0, 0, At, B0); PG8_MMA(0, 1, At, B1); PG8_BAR; PG8_SCHED;
;             PG8_LDA(At, 1, 1); PG8_STAGE(PG8_SB(1, 0), b3, voffB); PG8_STAGE(PG8_SB(1, 1), b3 + hstep, voffB); PG8_STAGE(PG8_SA(1, 0), a3, voffA);
;             PG8_WAIT_V(8); PG8_WAIT_L(0); PG8_BAR; PG8_MMA(1, 0, At, B0); PG8_MMA(1, 1, At, B1); PG8_BAR; PG8_SCHED;
	s_add_i32 s24, s51, s26
	v_lshl_add_u64 v[184:185], v[184:185], 0, s[6:7]
	s_mov_b32 m0, s24
	ds_read_b128 v[188:191], v154 offset:49152
	ds_read_b128 v[192:195], v154 offset:50176
	ds_read_b128 v[196:199], v154 offset:51200
	ds_read_b128 v[200:203], v154 offset:52224
	ds_read_b128 v[204:207], v154 offset:53248
	ds_read_b128 v[208:211], v154 offset:54272
	ds_read_b128 v[212:215], v154 offset:55296
	ds_read_b128 v[216:219], v154 offset:56320
	global_load_lds_dwordx4 v[184:185], off
	s_add_i32 m0, s24, 0x2000
	s_add_u32 s22, s22, 0x40080
	v_lshl_add_u64 v[184:185], v[220:221], 0, s[6:7]
	s_addc_u32 s23, s23, 0
	s_add_i32 s24, s52, s26
	global_load_lds_dwordx4 v[184:185], off
	v_lshl_add_u64 v[184:185], s[22:23], 0, v[134:135]
	s_mov_b32 m0, s24
	s_nop 0
	global_load_lds_dwordx4 v[184:185], off
	v_lshl_add_u64 v[184:185], s[22:23], 0, v[130:131]
	s_add_i32 m0, s24, 0x2000
	s_nop 0
	global_load_lds_dwordx4 v[184:185], off
	v_lshl_add_u64 v[184:185], v[222:223], 0, s[6:7]
	s_mov_b32 m0, s35
	s_nop 0
	global_load_lds_dwordx4 v[184:185], off
	v_lshl_add_u64 v[184:185], v[224:225], 0, s[6:7]
	s_mov_b32 m0, s36
	s_nop 0
	global_load_lds_dwordx4 v[184:185], off
	s_waitcnt vmcnt(8)
	s_waitcnt lgkmcnt(0)
	s_barrier
	s_waitcnt lgkmcnt(0)
	v_mfma_f32_16x16x32_bf16 v[62:65], v[146:149], v[188:191], v[62:65]
	v_mfma_f32_16x16x32_bf16 v[58:61], v[160:163], v[188:191], v[58:61]
	v_mfma_f32_16x16x32_bf16 v[46:49], v[146:149], v[196:199], v[46:49]
	v_mfma_f32_16x16x32_bf16 v[42:45], v[160:163], v[196:199], v[42:45]
	v_mfma_f32_16x16x32_bf16 v[30:33], v[146:149], v[204:207], v[30:33]
	v_mfma_f32_16x16x32_bf16 v[26:29], v[160:163], v[204:207], v[26:29]
	v_mfma_f32_16x16x32_bf16 v[14:17], v[146:149], v[212:215], v[14:17]
	v_mfma_f32_16x16x32_bf16 v[10:13], v[160:163], v[212:215], v[10:13]
	v_mfma_f32_16x16x32_bf16 v[62:65], v[156:159], v[192:195], v[62:65]
	v_mfma_f32_16x16x32_bf16 v[58:61], v[164:167], v[192:195], v[58:61]
	v_mfma_f32_16x16x32_bf16 v[46:49], v[156:159], v[200:203], v[46:49]
	v_mfma_f32_16x16x32_bf16 v[42:45], v[164:167], v[200:203], v[42:45]
	v_mfma_f32_16x16x32_bf16 v[30:33], v[156:159], v[208:211], v[30:33]
	v_mfma_f32_16x16x32_bf16 v[26:29], v[164:167], v[208:211], v[26:29]
	v_mfma_f32_16x16x32_bf16 v[14:17], v[156:159], v[216:219], v[14:17]
	v_mfma_f32_16x16x32_bf16 v[10:13], v[164:167], v[216:219], v[10:13]
	v_mfma_f32_16x16x32_bf16 v[54:57], v[168:171], v[188:191], v[54:57]
	v_mfma_f32_16x16x32_bf16 v[50:53], v[176:179], v[188:191], v[50:53]
	v_mfma_f32_16x16x32_bf16 v[38:41], v[168:171], v[196:199], v[38:41]
	v_mfma_f32_16x16x32_bf16 v[34:37], v[176:179], v[196:199], v[34:37]
	v_mfma_f32_16x16x32_bf16 v[22:25], v[168:171], v[204:207], v[22:25]
	v_mfma_f32_16x16x32_bf16 v[18:21], v[176:179], v[204:207], v[18:21]
	v_mfma_f32_16x16x32_bf16 v[6:9], v[168:171], v[212:215], v[6:9]
	v_mfma_f32_16x16x32_bf16 v[2:5], v[176:179], v[212:215], v[2:5]
	v_mfma_f32_16x16x32_bf16 v[54:57], v[172:175], v[192:195], v[54:57]
	v_mfma_f32_16x16x32_bf16 v[50:53], v[180:183], v[192:195], v[50:53]
	v_mfma_f32_16x16x32_bf16 v[38:41], v[172:175], v[200:203], v[38:41]
	v_mfma_f32_16x16x32_bf16 v[34:37], v[180:183], v[200:203], v[34:37]
	v_mfma_f32_16x16x32_bf16 v[22:25], v[172:175], v[208:211], v[22:25]
	v_mfma_f32_16x16x32_bf16 v[18:21], v[180:183], v[208:211], v[18:21]
	v_mfma_f32_16x16x32_bf16 v[6:9], v[172:175], v[216:219], v[6:9]
	v_mfma_f32_16x16x32_bf16 v[2:5], v[180:183], v[216:219], v[2:5]
	s_barrier
	s_add_i32 s50, s50, 2
	s_add_u32 s20, s20, 0x100
	s_addc_u32 s21, s21, 0
	s_add_u32 s48, s48, 0x100
	s_addc_u32 s49, s49, 0
	s_cmp_gt_u32 s50, 13
	s_cbranch_scc0 .LBB0_85
	s_and_b64 vcc, exec, s[8:9]
	s_cbranch_vccz .LBB0_88
	s_barrier

; #define PG8_WAIT_V(n) asm volatile("s_waitcnt vmcnt(" #n ")" ::: "memory")
; #define PG8_BAR __builtin_amdgcn_s_barrier()
; template <class Epi, class Sched, bool ALIGN_EPI = false, bool SP2 = false>
; __device__ __forceinline__ void gemm_phase(PG8_LAS unsigned char* lds, const Gemm g, const Sched& S, const Epi& E) {
;     ...
;     PG8_WAIT_V(0);
;     if constexpr (!ALIGN_EPI) { if (wr == 0) PG8_BAR; }
;     PG8_BAR;
.LBB0_91:
	s_setprio 0
	s_waitcnt vmcnt(0)
	s_barrier

; #define PG8_STAGE(bufoff, gbase, voff) do { _Pragma("unroll") for (int _i = 0; _i < 2; ++_i) \
;         __builtin_amdgcn_global_load_lds((const unsigned*)((const char*)(gbase) + (voff)[_i]), (PG8_LAS unsigned*)(lds + (bufoff) + ldsw + _i * 8192), 16, 0, 0); } while (0)
; #define PG8_BAR __builtin_amdgcn_s_barrier()
; template <class Epi, class Sched, bool ALIGN_EPI = false, bool SP2 = false>
; __device__ __forceinline__ void gemm_phase(PG8_LAS unsigned char* lds, const Gemm g, const Sched& S, const Epi& E) {
;     int tid_ = threadIdx.x; asm volatile("" : "+v"(tid_));
;     const int tid = tid_, wid = __builtin_amdgcn_readfirstlane(tid >> 6), lane = tid & 63, wr = wid >> 2, wc = wid & 3, fr = lane & 15, fq = lane >> 4;
;     const int K = g.K, LD = g.ld ? g.ld : g.K, nt = K / BK;
;     unsigned voffA[2], voffB[2];
; #pragma unroll
;     for (int i = 0; i < 2; ++i) { int R, C; stage_rc(tid * 16 + i * 8192, R, C); const int Rb = Epi::PERM ? ((R & ~31) + perm32(R & 31)) : R;
;         voffA[i] = (unsigned)(R * LD + C) * 2u; voffB[i] = (unsigned)(Rb * LD + C) * 2u; }
;     const size_t kstep = (size_t)(BK * 2);
;     const size_t hstep = (size_t)HALF * LD * 2;
;     const size_t tstep = 2 * hstep;
;     const unsigned ldsw = (unsigned)wid * 1024u;
;     const int aoff = lds_byte(wr * 64 + fr, fq * 8), boff = lds_byte(wc * 32 + fr, fq * 8);
;     ...
;     Unit cur, nxt; int ui = 0;
;     if (!S.next(0, cur)) return;
;     f32x4 acc[2][2][4][2];
; #pragma unroll
;     for (int a = 0; a < 2; ++a)
; #pragma unroll
;         for (int b = 0; b < 2; ++b)
; #pragma unroll
;             for (int m = 0; m < 4; ++m)
; #pragma unroll
;                 for (int n = 0; n < 2; ++n) acc[a][b][m][n] = (f32x4){0.f, 0.f, 0.f, 0.f};
;     bf16x8 At[4][2], B0[2][2], B1[2][2];
;     const size_t sstep = (size_t)K * 2;
;     const char* cA = (const char*)g.A + (size_t)cur.pm * tstep + (size_t)cur.pk * sstep; const char* cB = (const char*)g.Bt + (size_t)cur.pn * tstep + (size_t)cur.pk * sstep;
;     S.a_ready(cur);
;     if constexpr (SP2) {
;         PG8_STAGE(PG8_SB(0, 0), cB, voffB); PG8_STAGE(PG8_SB(0, 1), cB + hstep, voffB); PG8_STAGE(PG8_SA(0, 0), cA, voffA); PG8_STAGE(PG8_SA(0, 1), cA + hstep, voffA);
;         if (wr == 1) PG8_BAR;
.LBB0_1643:
	s_cmp_lt_i32 s46, 13
	s_cselect_b64 s[0:1], -1, 0
	s_cmp_gt_i32 s47, 12
	s_cselect_b64 s[2:3], -1, 0
	s_and_b64 s[0:1], s[0:1], s[2:3]
	s_andn2_b64 vcc, exec, s[0:1]
	s_cbranch_vccnz .LBB0_1718
	s_waitcnt vmcnt(0)
	v_mov_b32_e32 v11, v0
	s_cmpk_gt_i32 s33, 0xb57
	v_readfirstlane_b32 s3, v11
	s_cbranch_scc1 .LBB0_1660
	v_readlane_b32 s98, v254, 9
	s_cmp_lt_u32 s98, 4
	s_cbranch_scc1 .Lmy_prio_p12
	s_setprio 1
.Lmy_prio_p12:
	v_lshlrev_b32_e32 v1, 4, v11
	v_add_u32_e32 v2, 0x2000, v1
	v_ashrrev_i32_e32 v3, 31, v2
	v_lshrrev_b32_e32 v3, 22, v3
	v_add_u32_e32 v3, v2, v3
	v_ashrrev_i32_e32 v10, 10, v3
	v_mul_i32_i24_e32 v3, 0x400, v10
	v_sub_u32_e32 v2, v2, v3
	v_lshrrev_b32_e32 v3, 4, v2
	v_bitop3_b32 v2, v3, v2, 32 bitop3:0x6c
	v_ashrrev_i32_e32 v3, 31, v2
	v_lshrrev_b32_e32 v3, 26, v3
	v_add_u32_e32 v3, v2, v3
	v_lshlrev_b32_e32 v4, 3, v10
	v_ashrrev_i32_e32 v12, 6, v3
	v_and_b32_e32 v4, -16, v4
	v_add_u32_e32 v4, v12, v4
	v_and_b32_e32 v5, 3, v12
	s_mov_b32 s2, 0x1fffe0
	v_lshrrev_b32_e32 v6, 2, v4
	v_lshlrev_b32_e32 v7, 1, v4
	v_and_b32_e32 v3, 0xc0, v3
	v_and_or_b32 v5, v4, s2, v5
	v_and_b32_e32 v6, 4, v6
	v_and_b32_e32 v7, 24, v7
	v_sub_u32_e32 v2, v2, v3
	v_mov_b32_e32 v3, 1
	v_or3_b32 v5, v5, v6, v7
	v_lshlrev_b32_e32 v6, 5, v10
	v_ashrrev_i16_sdwa v2, v3, sext(v2) dst_sel:DWORD dst_unused:UNUSED_PAD src0_sel:DWORD src1_sel:BYTE_0
	v_and_b32_e32 v6, 32, v6
	v_bfe_i32 v13, v2, 0, 16
	v_add_lshl_u32 v2, v6, v13, 1
	v_lshl_add_u32 v130, v5, 11, v2
	v_lshl_add_u32 v132, v4, 11, v2
	v_bfe_i32 v2, v11, 27, 1
	v_lshrrev_b32_e32 v2, 22, v2
	v_add_u32_e32 v2, v1, v2
	v_and_b32_e32 v2, 0xfffffc00, v2
	v_sub_u32_e32 v1, v1, v2
	v_lshrrev_b32_e32 v2, 4, v1
	v_ashrrev_i32_e32 v4, 31, v11
	v_bitop3_b32 v1, v2, v1, 32 bitop3:0x6c
	v_lshrrev_b32_e32 v4, 26, v4
	v_ashrrev_i32_e32 v2, 31, v1
	v_add_u32_e32 v4, v11, v4
	v_lshrrev_b32_e32 v2, 26, v2
	v_ashrrev_i32_e32 v15, 6, v4
	v_add_u32_e32 v2, v1, v2
	v_lshlrev_b32_e32 v4, 3, v15
	s_add_u32 s0, s44, 0x1300000
	v_ashrrev_i32_e32 v14, 6, v2
	v_and_b32_e32 v4, -16, v4
	s_addc_u32 s1, s45, 0
	v_add_u32_e32 v4, v14, v4
	v_and_b32_e32 v5, 3, v14
	s_ashr_i32 s27, s33, 31
	v_and_or_b32 v5, v4, s2, v5
	s_lshr_b32 s2, s27, 29
	s_add_i32 s2, s33, s2
	s_waitcnt lgkmcnt(0)
	s_ashr_i32 s6, s3, 6
	s_ashr_i32 s4, s2, 3
	s_and_b32 s2, s2, -8
	s_ashr_i32 s8, s3, 8
	s_lshl_b32 s26, s6, 10
	s_sub_i32 s2, s33, s2
	s_cmp_lt_i32 s2, 0
	s_movk_i32 s28, 0x16c
	s_cselect_b32 s5, s28, 0x16b
	s_mul_i32 s2, s2, s5
	s_add_i32 s2, s2, s4
	s_mul_hi_i32 s4, s2, 0x2e8ba2e9
	s_lshr_b32 s5, s4, 31
	s_ashr_i32 s4, s4, 5
	v_lshrrev_b32_e32 v6, 2, v4
	v_lshlrev_b32_e32 v7, 1, v4
	v_and_b32_e32 v2, 0xc0, v2
	s_add_i32 s4, s4, s5
	v_and_b32_e32 v6, 4, v6
	v_and_b32_e32 v7, 24, v7
	v_sub_u32_e32 v1, v1, v2
	s_lshl_b32 s7, s4, 3
	v_or3_b32 v5, v5, v6, v7
	v_lshlrev_b32_e32 v6, 5, v15
	v_ashrrev_i16_sdwa v1, v3, sext(v1) dst_sel:DWORD dst_unused:UNUSED_PAD src0_sel:DWORD src1_sel:BYTE_0
	s_sub_i32 s5, 0x84, s7
	s_mulk_i32 s4, 0xb0
	v_and_b32_e32 v6, 32, v6
	v_bfe_i32 v16, v1, 0, 16
	s_min_u32 s9, s5, 8
	s_sub_i32 s10, s2, s4
	v_add_lshl_u32 v1, v6, v16, 1
	s_sext_i32_i16 s2, s10
	v_cvt_f32_ubyte0_e32 v3, s9
	v_lshl_add_u32 v134, v5, 11, v1
	v_cvt_f32_i32_e32 v2, s2
	v_rcp_iflag_f32_e32 v5, v3
	v_lshl_add_u32 v136, v4, 11, v1
	s_ashr_i32 s2, s2, 30
	s_or_b32 s2, s2, 1
	v_mul_f32_e32 v1, v2, v5
	v_trunc_f32_e32 v1, v1
	v_fma_f32 v2, -v1, v3, v2
	v_cvt_i32_f32_e32 v1, v1
	v_cmp_ge_f32_e64 s[4:5], |v2|, v3
	s_and_b64 s[4:5], s[4:5], exec
	s_cselect_b32 s2, s2, 0
	v_readfirstlane_b32 s4, v1
	s_add_i32 s2, s4, s2
	s_mul_i32 s4, s2, s9
	s_sub_i32 s4, s10, s4
	s_sext_i32_i16 s4, s4
	s_add_i32 s18, s7, s4
	s_ashr_i32 s19, s18, 31
	s_bfe_i64 s[10:11], s[2:3], 0x100000
	s_lshl_b64 s[4:5], s[18:19], 19
	s_lshl_b64 s[10:11], s[10:11], 19
	s_add_u32 s22, s0, s10
	s_addc_u32 s23, s1, s11
	s_add_i32 s19, s26, 0
	s_add_i32 m0, s19, 0x10000
	v_mov_b32_e32 v135, 0
	global_load_lds_dwordx4 v134, s[22:23]
	s_add_i32 m0, s19, 0x12000
	s_add_u32 s10, s22, 0x40000
	global_load_lds_dwordx4 v130, s[22:23]
	s_addc_u32 s11, s23, 0
	s_add_i32 m0, s19, 0x14000
	v_mov_b32_e32 v131, v135
	global_load_lds_dwordx4 v134, s[10:11]
	s_add_i32 m0, s19, 0x16000
	v_mov_b32_e32 v137, v135
	global_load_lds_dwordx4 v130, s[10:11]
	v_readlane_b32 s10, v254, 13
	v_readlane_b32 s11, v254, 14
	s_add_u32 s20, s10, s4
	s_addc_u32 s21, s11, s5
	s_add_i32 s29, s19, 0x2000
	s_mov_b32 m0, s19
	s_add_u32 s4, s20, 0x40000
	global_load_lds_dwordx4 v136, s[20:21]
	s_mov_b32 m0, s29
	s_addc_u32 s5, s21, 0
	s_add_i32 s30, s19, 0x4000
	global_load_lds_dwordx4 v132, s[20:21]
	s_mov_b32 m0, s30
	s_add_i32 s31, s19, 0x6000
	global_load_lds_dwordx4 v136, s[4:5]
	s_mov_b32 m0, s31
	v_mov_b32_e32 v133, v135
	global_load_lds_dwordx4 v132, s[4:5]
	s_cmp_eq_u32 s8, 1
	s_mov_b32 s34, 0
	v_lshl_add_u64 v[8:9], s[22:23], 0, v[134:135]
	v_lshl_add_u64 v[6:7], s[22:23], 0, v[130:131]
	v_lshl_add_u64 v[2:3], s[20:21], 0, v[136:137]
	s_cselect_b64 s[4:5], -1, 0
	s_cmp_lg_u32 s8, 1
	v_lshl_add_u64 v[4:5], s[20:21], 0, v[132:133]
	s_cbranch_scc1 .LBB0_1647
	s_barrier
